# L2 prefetch of the first pooling tile during the last attention chunk
# baseline (speedup 1.0000x reference)
; __device__ __forceinline__ unsigned cvtpk(float lo, float hi) { f32x2_t v = {lo, hi}; bf16x2_t b = __builtin_convertvector(v, bf16x2_t); return __builtin_bit_cast(unsigned, b); }
; __device__ __forceinline__ bool attn_unit(const Ptrs& P, LAS unsigned char* lds, int unit, int tid, int wave, int lane, bool pre, int nxt) {
;     ...
;         for (int kt = 0; kt < 4; ++kt) {
;             if (c == 0 && 32 * kt + 31 < q0) continue;
;             if (c == 2 && 32 * kt > q0 + 63) continue;
;             bf16x8_t kf[4], vf[2][2];
; #pragma unroll
;             for (int ds = 0; ds < 4; ++ds) kf[ds] = *(const LAS bf16x8_t*)(Kl + (32 * kt + r) * AT_KP + (16 * ds + 8 * hh) * 2);
; #pragma unroll
;             for (int db = 0; db < 2; ++db)
; #pragma unroll
;                 for (int s = 0; s < 2; ++s) vf[db][s] = *(const LAS bf16x8_t*)(Vl + (32 * db + r) * AT_VP + (32 * kt + 16 * s + 8 * hh) * 2);
; #pragma unroll
;             for (int cb = 0; cb < 2; ++cb) {
;                 const int dq = 32 * kt - (q0 + 32 * cb);
;                 if ((c == 0 && dq < 0) || (c == 2 && dq > 0)) continue;
;                 const bool diag = (c == 0 || c == 2) && dq == 0;
;                 f32x16 st = MFMA32(kf[0], qf[cb][0], negm);
;                 st = MFMA32(kf[1], qf[cb][1], st); st = MFMA32(kf[2], qf[cb][2], st); st = MFMA32(kf[3], qf[cb][3], st);
;                 float p[16];
; #pragma unroll
;                 for (int i = 0; i < 16; ++i) p[i] = __builtin_amdgcn_exp2f(st[i]);
;                 if (diag) {
;                     const int thr = r - 4 * hh;
; #pragma unroll
;                     for (int i = 0; i < 16; ++i) { const bool vis = c == 0 ? crow(i, 0) >= thr : crow(i, 0) <= thr; p[i] = vis ? p[i] : 0.f; }
;                 }
;                 float s4 = 0.f;
; #pragma unroll
;                 for (int i = 0; i < 16; ++i) s4 += p[i];
;                 rs[cb] += s4;
; #pragma unroll
;                 for (int s = 0; s < 2; ++s) {
;                     u32x4 w; w.x = cvtpk(p[8 * s], p[8 * s + 1]); w.y = cvtpk(p[8 * s + 2], p[8 * s + 3]); w.z = cvtpk(p[8 * s + 4], p[8 * s + 5]); w.w = cvtpk(p[8 * s + 6], p[8 * s + 7]);
;                     const bf16x8_t pb = __builtin_bit_cast(bf16x8_t, w);
;                     o[0][cb] = MFMA32(vf[0][s], pb, o[0][cb]); o[1][cb] = MFMA32(vf[1][s], pb, o[1][cb]);
;                 }
;             }
;         }
.LBB9_400:
	ds_read_b128 v[238:241], v196 offset:0
	ds_read_b128 v[242:245], v196 offset:32
	ds_read_b128 v[246:249], v196 offset:64
	ds_read_b128 v[204:207], v196 offset:96
	s_waitcnt lgkmcnt(0)
	v_mfma_f32_32x32x16_bf16 v[82:97], v[238:241], v[114:117], v[18:33]
	v_mfma_f32_32x32x16_bf16 v[82:97], v[242:245], v[118:121], v[82:97]
	v_mfma_f32_32x32x16_bf16 v[82:97], v[246:249], v[122:125], v[82:97]
	v_mfma_f32_32x32x16_bf16 v[82:97], v[204:207], v[126:129], v[82:97]
	v_mfma_f32_32x32x16_bf16 v[98:113], v[238:241], v[130:133], v[18:33]
	v_mfma_f32_32x32x16_bf16 v[98:113], v[242:245], v[134:137], v[98:113]
	v_mfma_f32_32x32x16_bf16 v[98:113], v[246:249], v[138:141], v[98:113]
	v_mfma_f32_32x32x16_bf16 v[98:113], v[204:207], v[142:145], v[98:113]
	ds_read_b128 v[146:149], v195 offset:0
	ds_read_b128 v[150:153], v195 offset:32
	ds_read_b128 v[154:157], v194 offset:0
	ds_read_b128 v[158:161], v194 offset:32
	ds_read_b128 v[238:241], v196 offset:4608
	ds_read_b128 v[242:245], v196 offset:4640
	ds_read_b128 v[246:249], v196 offset:4672
	ds_read_b128 v[204:207], v196 offset:4704
	v_exp_f32_e32 v82, v82
	v_exp_f32_e32 v83, v83
	v_exp_f32_e32 v84, v84
	v_exp_f32_e32 v85, v85
	v_exp_f32_e32 v86, v86
	v_exp_f32_e32 v87, v87
	v_exp_f32_e32 v88, v88
	v_exp_f32_e32 v89, v89
	v_exp_f32_e32 v90, v90
	v_exp_f32_e32 v91, v91
	v_exp_f32_e32 v92, v92
	v_exp_f32_e32 v93, v93
	v_exp_f32_e32 v94, v94
	v_exp_f32_e32 v95, v95
	v_exp_f32_e32 v96, v96
	v_exp_f32_e32 v97, v97
	v_add_f32_e32 v183, v82, v183
	v_add_f32_e32 v183, v83, v183
	v_add_f32_e32 v183, v84, v183
	v_add_f32_e32 v183, v85, v183
	v_add_f32_e32 v183, v86, v183
	v_add_f32_e32 v183, v87, v183
	v_add_f32_e32 v183, v88, v183
	v_add_f32_e32 v183, v89, v183
	v_add_f32_e32 v183, v90, v183
	v_add_f32_e32 v183, v91, v183
	v_add_f32_e32 v183, v92, v183
	v_add_f32_e32 v183, v93, v183
	v_add_f32_e32 v183, v94, v183
	v_add_f32_e32 v183, v95, v183
	v_add_f32_e32 v183, v96, v183
	v_add_f32_e32 v183, v97, v183
	v_cvt_pk_bf16_f32 v82, v82, v83
	v_cvt_pk_bf16_f32 v83, v84, v85
	v_cvt_pk_bf16_f32 v84, v86, v87
	v_cvt_pk_bf16_f32 v85, v88, v89
	v_cvt_pk_bf16_f32 v86, v90, v91
	v_cvt_pk_bf16_f32 v87, v92, v93
	v_cvt_pk_bf16_f32 v88, v94, v95
	v_cvt_pk_bf16_f32 v89, v96, v97
	s_nop 0
	s_waitcnt lgkmcnt(4)
	v_mfma_f32_32x32x16_bf16 v[66:81], v[146:149], v[82:85], v[66:81]
	v_mfma_f32_32x32x16_bf16 v[50:65], v[154:157], v[82:85], v[50:65]
	v_exp_f32_e32 v98, v98
	v_exp_f32_e32 v99, v99
	v_exp_f32_e32 v100, v100
	v_exp_f32_e32 v101, v101
	v_exp_f32_e32 v102, v102
	v_mfma_f32_32x32x16_bf16 v[66:81], v[150:153], v[86:89], v[66:81]
	v_exp_f32_e32 v103, v103
	v_exp_f32_e32 v104, v104
	v_exp_f32_e32 v105, v105
	v_exp_f32_e32 v106, v106
	v_exp_f32_e32 v107, v107
	v_mfma_f32_32x32x16_bf16 v[50:65], v[158:161], v[86:89], v[50:65]
	v_exp_f32_e32 v108, v108
	v_exp_f32_e32 v109, v109
	v_exp_f32_e32 v110, v110
	v_exp_f32_e32 v111, v111
	v_exp_f32_e32 v112, v112
	s_waitcnt lgkmcnt(0)
	v_mfma_f32_32x32x16_bf16 v[82:97], v[238:241], v[114:117], v[18:33]
	v_exp_f32_e32 v113, v113
	v_add_f32_e32 v182, v98, v182
	v_add_f32_e32 v182, v99, v182
	v_add_f32_e32 v182, v100, v182
	v_add_f32_e32 v182, v101, v182
	v_mfma_f32_32x32x16_bf16 v[82:97], v[242:245], v[118:121], v[82:97]
	v_add_f32_e32 v182, v102, v182
	v_add_f32_e32 v182, v103, v182
	v_add_f32_e32 v182, v104, v182
	v_add_f32_e32 v182, v105, v182
	v_add_f32_e32 v182, v106, v182
	v_mfma_f32_32x32x16_bf16 v[82:97], v[246:249], v[122:125], v[82:97]
	v_add_f32_e32 v182, v107, v182
	v_add_f32_e32 v182, v108, v182
	v_add_f32_e32 v182, v109, v182
	v_add_f32_e32 v182, v110, v182
	v_add_f32_e32 v182, v111, v182
	v_mfma_f32_32x32x16_bf16 v[82:97], v[204:207], v[126:129], v[82:97]
	v_add_f32_e32 v182, v112, v182
	v_add_f32_e32 v182, v113, v182
	v_cvt_pk_bf16_f32 v98, v98, v99
	v_cvt_pk_bf16_f32 v99, v100, v101
	v_cvt_pk_bf16_f32 v100, v102, v103
	v_cvt_pk_bf16_f32 v101, v104, v105
	v_cvt_pk_bf16_f32 v102, v106, v107
	v_cvt_pk_bf16_f32 v103, v108, v109
	v_cvt_pk_bf16_f32 v104, v110, v111
	v_cvt_pk_bf16_f32 v105, v112, v113
	s_nop 0
	v_mfma_f32_32x32x16_bf16 v[34:49], v[146:149], v[98:101], v[34:49]
	v_mfma_f32_32x32x16_bf16 v[2:17], v[154:157], v[98:101], v[2:17]
	v_exp_f32_e32 v82, v82
	v_exp_f32_e32 v83, v83
	v_exp_f32_e32 v84, v84
	v_exp_f32_e32 v85, v85
	v_exp_f32_e32 v86, v86
	v_mfma_f32_32x32x16_bf16 v[34:49], v[150:153], v[102:105], v[34:49]
	v_exp_f32_e32 v87, v87
	v_exp_f32_e32 v88, v88
	v_exp_f32_e32 v89, v89
	v_exp_f32_e32 v90, v90
	v_exp_f32_e32 v91, v91
	v_mfma_f32_32x32x16_bf16 v[2:17], v[158:161], v[102:105], v[2:17]
	ds_read_b128 v[146:149], v195 offset:64
	ds_read_b128 v[150:153], v195 offset:96
	ds_read_b128 v[154:157], v194 offset:64
	ds_read_b128 v[158:161], v194 offset:96
	v_exp_f32_e32 v92, v92
	v_exp_f32_e32 v93, v93
	v_exp_f32_e32 v94, v94
	v_exp_f32_e32 v95, v95
	v_exp_f32_e32 v96, v96
	v_mfma_f32_32x32x16_bf16 v[98:113], v[238:241], v[130:133], v[18:33]
	v_exp_f32_e32 v97, v97
	v_add_f32_e32 v183, v82, v183
	v_add_f32_e32 v183, v83, v183
	v_add_f32_e32 v183, v84, v183
	v_add_f32_e32 v183, v85, v183
	v_mfma_f32_32x32x16_bf16 v[98:113], v[242:245], v[134:137], v[98:113]
	v_add_f32_e32 v183, v86, v183
	v_add_f32_e32 v183, v87, v183
	v_add_f32_e32 v183, v88, v183
	v_add_f32_e32 v183, v89, v183
	v_add_f32_e32 v183, v90, v183
	v_mfma_f32_32x32x16_bf16 v[98:113], v[246:249], v[138:141], v[98:113]
	v_add_f32_e32 v183, v91, v183
	v_add_f32_e32 v183, v92, v183
	v_add_f32_e32 v183, v93, v183
	v_add_f32_e32 v183, v94, v183
	v_add_f32_e32 v183, v95, v183
	v_mfma_f32_32x32x16_bf16 v[98:113], v[204:207], v[142:145], v[98:113]
	ds_read_b128 v[238:241], v196 offset:9216
	ds_read_b128 v[242:245], v196 offset:9248
	ds_read_b128 v[246:249], v196 offset:9280
	ds_read_b128 v[204:207], v196 offset:9312
	v_add_f32_e32 v183, v96, v183
	v_add_f32_e32 v183, v97, v183
	v_cvt_pk_bf16_f32 v82, v82, v83
	v_cvt_pk_bf16_f32 v83, v84, v85
	v_cvt_pk_bf16_f32 v84, v86, v87
	v_cvt_pk_bf16_f32 v85, v88, v89
	v_cvt_pk_bf16_f32 v86, v90, v91
	v_cvt_pk_bf16_f32 v87, v92, v93
	v_cvt_pk_bf16_f32 v88, v94, v95
	v_cvt_pk_bf16_f32 v89, v96, v97
	s_nop 0
	s_waitcnt lgkmcnt(4)
; __device__ __forceinline__ unsigned cvtpk(float lo, float hi) { f32x2_t v = {lo, hi}; bf16x2_t b = __builtin_convertvector(v, bf16x2_t); return __builtin_bit_cast(unsigned, b); }
; __device__ __forceinline__ bool attn_unit(const Ptrs& P, LAS unsigned char* lds, int unit, int tid, int wave, int lane, bool pre, int nxt) {
;     ...
;         for (int kt = 0; kt < 4; ++kt) {
;             if (c == 0 && 32 * kt + 31 < q0) continue;
;             if (c == 2 && 32 * kt > q0 + 63) continue;
;             bf16x8_t kf[4], vf[2][2];
; #pragma unroll
;             for (int ds = 0; ds < 4; ++ds) kf[ds] = *(const LAS bf16x8_t*)(Kl + (32 * kt + r) * AT_KP + (16 * ds + 8 * hh) * 2);
; #pragma unroll
;             for (int db = 0; db < 2; ++db)
; #pragma unroll
;                 for (int s = 0; s < 2; ++s) vf[db][s] = *(const LAS bf16x8_t*)(Vl + (32 * db + r) * AT_VP + (32 * kt + 16 * s + 8 * hh) * 2);
; #pragma unroll
;             for (int cb = 0; cb < 2; ++cb) {
;                 const int dq = 32 * kt - (q0 + 32 * cb);
;                 if ((c == 0 && dq < 0) || (c == 2 && dq > 0)) continue;
;                 const bool diag = (c == 0 || c == 2) && dq == 0;
;                 f32x16 st = MFMA32(kf[0], qf[cb][0], negm);
;                 st = MFMA32(kf[1], qf[cb][1], st); st = MFMA32(kf[2], qf[cb][2], st); st = MFMA32(kf[3], qf[cb][3], st);
;                 float p[16];
; #pragma unroll
;                 for (int i = 0; i < 16; ++i) p[i] = __builtin_amdgcn_exp2f(st[i]);
;                 if (diag) {
;                     const int thr = r - 4 * hh;
; #pragma unroll
;                     for (int i = 0; i < 16; ++i) { const bool vis = c == 0 ? crow(i, 0) >= thr : crow(i, 0) <= thr; p[i] = vis ? p[i] : 0.f; }
;                 }
;                 float s4 = 0.f;
; #pragma unroll
;                 for (int i = 0; i < 16; ++i) s4 += p[i];
;                 rs[cb] += s4;
; #pragma unroll
;                 for (int s = 0; s < 2; ++s) {
;                     u32x4 w; w.x = cvtpk(p[8 * s], p[8 * s + 1]); w.y = cvtpk(p[8 * s + 2], p[8 * s + 3]); w.z = cvtpk(p[8 * s + 4], p[8 * s + 5]); w.w = cvtpk(p[8 * s + 6], p[8 * s + 7]);
;                     const bf16x8_t pb = __builtin_bit_cast(bf16x8_t, w);
;                     o[0][cb] = MFMA32(vf[0][s], pb, o[0][cb]); o[1][cb] = MFMA32(vf[1][s], pb, o[1][cb]);
;                 }
;             }
;         }
	v_mfma_f32_32x32x16_bf16 v[66:81], v[146:149], v[82:85], v[66:81]
	v_mfma_f32_32x32x16_bf16 v[50:65], v[154:157], v[82:85], v[50:65]
	v_exp_f32_e32 v98, v98
	v_exp_f32_e32 v99, v99
	v_exp_f32_e32 v100, v100
	v_exp_f32_e32 v101, v101
	v_exp_f32_e32 v102, v102
	v_mfma_f32_32x32x16_bf16 v[66:81], v[150:153], v[86:89], v[66:81]
	v_exp_f32_e32 v103, v103
	v_exp_f32_e32 v104, v104
	v_exp_f32_e32 v105, v105
	v_exp_f32_e32 v106, v106
	v_exp_f32_e32 v107, v107
	v_mfma_f32_32x32x16_bf16 v[50:65], v[158:161], v[86:89], v[50:65]
	v_exp_f32_e32 v108, v108
	v_exp_f32_e32 v109, v109
	v_exp_f32_e32 v110, v110
	v_exp_f32_e32 v111, v111
	v_exp_f32_e32 v112, v112
	s_waitcnt lgkmcnt(0)
	v_mfma_f32_32x32x16_bf16 v[82:97], v[238:241], v[114:117], v[18:33]
	v_exp_f32_e32 v113, v113
	v_add_f32_e32 v182, v98, v182
	v_add_f32_e32 v182, v99, v182
	v_add_f32_e32 v182, v100, v182
	v_add_f32_e32 v182, v101, v182
	v_mfma_f32_32x32x16_bf16 v[82:97], v[242:245], v[118:121], v[82:97]
	v_add_f32_e32 v182, v102, v182
	v_add_f32_e32 v182, v103, v182
	v_add_f32_e32 v182, v104, v182
	v_add_f32_e32 v182, v105, v182
	v_add_f32_e32 v182, v106, v182
	v_mfma_f32_32x32x16_bf16 v[82:97], v[246:249], v[122:125], v[82:97]
	v_add_f32_e32 v182, v107, v182
	v_add_f32_e32 v182, v108, v182
	v_add_f32_e32 v182, v109, v182
	v_add_f32_e32 v182, v110, v182
	v_add_f32_e32 v182, v111, v182
	v_mfma_f32_32x32x16_bf16 v[82:97], v[204:207], v[126:129], v[82:97]
	v_add_f32_e32 v182, v112, v182
	v_add_f32_e32 v182, v113, v182
	v_cvt_pk_bf16_f32 v98, v98, v99
	v_cvt_pk_bf16_f32 v99, v100, v101
	v_cvt_pk_bf16_f32 v100, v102, v103
	v_cvt_pk_bf16_f32 v101, v104, v105
	v_cvt_pk_bf16_f32 v102, v106, v107
	v_cvt_pk_bf16_f32 v103, v108, v109
	v_cvt_pk_bf16_f32 v104, v110, v111
	v_cvt_pk_bf16_f32 v105, v112, v113
	s_nop 0
	v_mfma_f32_32x32x16_bf16 v[34:49], v[146:149], v[98:101], v[34:49]
	v_mfma_f32_32x32x16_bf16 v[2:17], v[154:157], v[98:101], v[2:17]
	v_exp_f32_e32 v82, v82
	v_exp_f32_e32 v83, v83
	v_exp_f32_e32 v84, v84
	v_exp_f32_e32 v85, v85
	v_exp_f32_e32 v86, v86
	v_mfma_f32_32x32x16_bf16 v[34:49], v[150:153], v[102:105], v[34:49]
	v_exp_f32_e32 v87, v87
	v_exp_f32_e32 v88, v88
	v_exp_f32_e32 v89, v89
	v_exp_f32_e32 v90, v90
	v_exp_f32_e32 v91, v91
	v_mfma_f32_32x32x16_bf16 v[2:17], v[158:161], v[102:105], v[2:17]
	ds_read_b128 v[146:149], v195 offset:128
	ds_read_b128 v[150:153], v195 offset:160
	ds_read_b128 v[154:157], v194 offset:128
	ds_read_b128 v[158:161], v194 offset:160
	v_exp_f32_e32 v92, v92
	v_exp_f32_e32 v93, v93
	v_exp_f32_e32 v94, v94
	v_exp_f32_e32 v95, v95
	v_exp_f32_e32 v96, v96
	v_mfma_f32_32x32x16_bf16 v[98:113], v[238:241], v[130:133], v[18:33]
	v_exp_f32_e32 v97, v97
	v_add_f32_e32 v183, v82, v183
	v_add_f32_e32 v183, v83, v183
	v_add_f32_e32 v183, v84, v183
	v_add_f32_e32 v183, v85, v183
	v_mfma_f32_32x32x16_bf16 v[98:113], v[242:245], v[134:137], v[98:113]
	v_add_f32_e32 v183, v86, v183
	v_add_f32_e32 v183, v87, v183
	v_add_f32_e32 v183, v88, v183
	v_add_f32_e32 v183, v89, v183
	v_add_f32_e32 v183, v90, v183
	v_mfma_f32_32x32x16_bf16 v[98:113], v[246:249], v[138:141], v[98:113]
	v_add_f32_e32 v183, v91, v183
	v_add_f32_e32 v183, v92, v183
	v_add_f32_e32 v183, v93, v183
	v_add_f32_e32 v183, v94, v183
	v_add_f32_e32 v183, v95, v183
	v_mfma_f32_32x32x16_bf16 v[98:113], v[204:207], v[142:145], v[98:113]
	ds_read_b128 v[238:241], v196 offset:13824
	ds_read_b128 v[242:245], v196 offset:13856
	ds_read_b128 v[246:249], v196 offset:13888
	ds_read_b128 v[204:207], v196 offset:13920
	v_add_f32_e32 v183, v96, v183
	v_add_f32_e32 v183, v97, v183
	v_cvt_pk_bf16_f32 v82, v82, v83
	v_cvt_pk_bf16_f32 v83, v84, v85
	v_cvt_pk_bf16_f32 v84, v86, v87
	v_cvt_pk_bf16_f32 v85, v88, v89
	v_cvt_pk_bf16_f32 v86, v90, v91
	v_cvt_pk_bf16_f32 v87, v92, v93
	v_cvt_pk_bf16_f32 v88, v94, v95
	v_cvt_pk_bf16_f32 v89, v96, v97
	s_nop 0
	s_waitcnt lgkmcnt(4)
	v_mfma_f32_32x32x16_bf16 v[66:81], v[146:149], v[82:85], v[66:81]
	v_mfma_f32_32x32x16_bf16 v[50:65], v[154:157], v[82:85], v[50:65]
	v_exp_f32_e32 v98, v98
	v_exp_f32_e32 v99, v99
	v_exp_f32_e32 v100, v100
	v_exp_f32_e32 v101, v101
	v_exp_f32_e32 v102, v102
	v_mfma_f32_32x32x16_bf16 v[66:81], v[150:153], v[86:89], v[66:81]
	v_exp_f32_e32 v103, v103
	v_exp_f32_e32 v104, v104
	v_exp_f32_e32 v105, v105
	v_exp_f32_e32 v106, v106
	v_exp_f32_e32 v107, v107
	v_mfma_f32_32x32x16_bf16 v[50:65], v[158:161], v[86:89], v[50:65]
	v_exp_f32_e32 v108, v108
	v_exp_f32_e32 v109, v109
	v_exp_f32_e32 v110, v110
	v_exp_f32_e32 v111, v111
	v_exp_f32_e32 v112, v112
	s_waitcnt lgkmcnt(0)
; __device__ __forceinline__ unsigned cvtpk(float lo, float hi) { f32x2_t v = {lo, hi}; bf16x2_t b = __builtin_convertvector(v, bf16x2_t); return __builtin_bit_cast(unsigned, b); }
; __device__ __forceinline__ int crow(int reg, int h) { return (reg & 3) + 8 * (reg >> 2) + 4 * h; }
; #define MFMA32(a, b, c) __builtin_amdgcn_mfma_f32_32x32x16_bf16((a), (b), (c), 0, 0, 0)
; #define AT_SYNC() do { asm volatile("s_waitcnt vmcnt(0) lgkmcnt(0)" ::: "memory"); __builtin_amdgcn_s_barrier(); asm volatile("" ::: "memory"); } while (0)
; __device__ __forceinline__ bool attn_unit(const Ptrs& P, LAS unsigned char* lds, int unit, int tid, int wave, int lane, bool pre, int nxt) {
;     ...
;             for (int cb = 0; cb < 2; ++cb) {
;                 const int dq = 32 * kt - (q0 + 32 * cb);
;                 if ((c == 0 && dq < 0) || (c == 2 && dq > 0)) continue;
;                 const bool diag = (c == 0 || c == 2) && dq == 0;
;                 f32x16 st = MFMA32(kf[0], qf[cb][0], negm);
;                 st = MFMA32(kf[1], qf[cb][1], st); st = MFMA32(kf[2], qf[cb][2], st); st = MFMA32(kf[3], qf[cb][3], st);
;                 float p[16];
; #pragma unroll
;                 for (int i = 0; i < 16; ++i) p[i] = __builtin_amdgcn_exp2f(st[i]);
;                 if (diag) {
;                     const int thr = r - 4 * hh;
; #pragma unroll
;                     for (int i = 0; i < 16; ++i) { const bool vis = c == 0 ? crow(i, 0) >= thr : crow(i, 0) <= thr; p[i] = vis ? p[i] : 0.f; }
;                 }
;                 float s4 = 0.f;
; #pragma unroll
;                 for (int i = 0; i < 16; ++i) s4 += p[i];
;                 rs[cb] += s4;
; #pragma unroll
;                 for (int s = 0; s < 2; ++s) {
;                     u32x4 w; w.x = cvtpk(p[8 * s], p[8 * s + 1]); w.y = cvtpk(p[8 * s + 2], p[8 * s + 3]); w.z = cvtpk(p[8 * s + 4], p[8 * s + 5]); w.w = cvtpk(p[8 * s + 6], p[8 * s + 7]);
;                     const bf16x8_t pb = __builtin_bit_cast(bf16x8_t, w);
;                     o[0][cb] = MFMA32(vf[0][s], pb, o[0][cb]); o[1][cb] = MFMA32(vf[1][s], pb, o[1][cb]);
;                 }
;             }
;         }
;         AT_SYNC();
	v_mfma_f32_32x32x16_bf16 v[82:97], v[238:241], v[114:117], v[18:33]
	v_exp_f32_e32 v113, v113
	v_add_f32_e32 v182, v98, v182
	v_add_f32_e32 v182, v99, v182
	v_add_f32_e32 v182, v100, v182
	v_add_f32_e32 v182, v101, v182
	v_mfma_f32_32x32x16_bf16 v[82:97], v[242:245], v[118:121], v[82:97]
	v_add_f32_e32 v182, v102, v182
	v_add_f32_e32 v182, v103, v182
	v_add_f32_e32 v182, v104, v182
	v_add_f32_e32 v182, v105, v182
	v_add_f32_e32 v182, v106, v182
	v_mfma_f32_32x32x16_bf16 v[82:97], v[246:249], v[122:125], v[82:97]
	v_add_f32_e32 v182, v107, v182
	v_add_f32_e32 v182, v108, v182
	v_add_f32_e32 v182, v109, v182
	v_add_f32_e32 v182, v110, v182
	v_add_f32_e32 v182, v111, v182
	v_mfma_f32_32x32x16_bf16 v[82:97], v[204:207], v[126:129], v[82:97]
	v_add_f32_e32 v182, v112, v182
	v_add_f32_e32 v182, v113, v182
	v_cvt_pk_bf16_f32 v98, v98, v99
	v_cvt_pk_bf16_f32 v99, v100, v101
	v_cvt_pk_bf16_f32 v100, v102, v103
	v_cvt_pk_bf16_f32 v101, v104, v105
	v_cvt_pk_bf16_f32 v102, v106, v107
	v_cvt_pk_bf16_f32 v103, v108, v109
	v_cvt_pk_bf16_f32 v104, v110, v111
	v_cvt_pk_bf16_f32 v105, v112, v113
	s_nop 0
	v_mfma_f32_32x32x16_bf16 v[34:49], v[146:149], v[98:101], v[34:49]
	v_mfma_f32_32x32x16_bf16 v[2:17], v[154:157], v[98:101], v[2:17]
	v_exp_f32_e32 v82, v82
	v_exp_f32_e32 v83, v83
	v_exp_f32_e32 v84, v84
	v_exp_f32_e32 v85, v85
	v_exp_f32_e32 v86, v86
	v_mfma_f32_32x32x16_bf16 v[34:49], v[150:153], v[102:105], v[34:49]
	v_exp_f32_e32 v87, v87
	v_exp_f32_e32 v88, v88
	v_exp_f32_e32 v89, v89
	v_exp_f32_e32 v90, v90
	v_exp_f32_e32 v91, v91
	v_mfma_f32_32x32x16_bf16 v[2:17], v[158:161], v[102:105], v[2:17]
	ds_read_b128 v[146:149], v195 offset:192
	ds_read_b128 v[150:153], v195 offset:224
	ds_read_b128 v[154:157], v194 offset:192
	ds_read_b128 v[158:161], v194 offset:224
	v_exp_f32_e32 v92, v92
	v_exp_f32_e32 v93, v93
	v_exp_f32_e32 v94, v94
	v_exp_f32_e32 v95, v95
	v_exp_f32_e32 v96, v96
	v_mfma_f32_32x32x16_bf16 v[98:113], v[238:241], v[130:133], v[18:33]
	v_exp_f32_e32 v97, v97
	v_add_f32_e32 v183, v82, v183
	v_add_f32_e32 v183, v83, v183
	v_add_f32_e32 v183, v84, v183
	v_add_f32_e32 v183, v85, v183
	v_mfma_f32_32x32x16_bf16 v[98:113], v[242:245], v[134:137], v[98:113]
	v_add_f32_e32 v183, v86, v183
	v_add_f32_e32 v183, v87, v183
	v_add_f32_e32 v183, v88, v183
	v_add_f32_e32 v183, v89, v183
	v_add_f32_e32 v183, v90, v183
	v_mfma_f32_32x32x16_bf16 v[98:113], v[246:249], v[138:141], v[98:113]
	v_add_f32_e32 v183, v91, v183
	v_add_f32_e32 v183, v92, v183
	v_add_f32_e32 v183, v93, v183
	v_add_f32_e32 v183, v94, v183
	v_add_f32_e32 v183, v95, v183
	v_mfma_f32_32x32x16_bf16 v[98:113], v[204:207], v[142:145], v[98:113]
	v_add_f32_e32 v183, v96, v183
	v_add_f32_e32 v183, v97, v183
	v_cvt_pk_bf16_f32 v82, v82, v83
	v_cvt_pk_bf16_f32 v83, v84, v85
	v_cvt_pk_bf16_f32 v84, v86, v87
	v_cvt_pk_bf16_f32 v85, v88, v89
	v_cvt_pk_bf16_f32 v86, v90, v91
	v_cvt_pk_bf16_f32 v87, v92, v93
	v_cvt_pk_bf16_f32 v88, v94, v95
	v_cvt_pk_bf16_f32 v89, v96, v97
	s_nop 0
	s_waitcnt lgkmcnt(0)
	v_mfma_f32_32x32x16_bf16 v[66:81], v[146:149], v[82:85], v[66:81]
	v_mfma_f32_32x32x16_bf16 v[50:65], v[154:157], v[82:85], v[50:65]
	v_exp_f32_e32 v98, v98
	v_exp_f32_e32 v99, v99
	v_exp_f32_e32 v100, v100
	v_exp_f32_e32 v101, v101
	v_exp_f32_e32 v102, v102
	v_mfma_f32_32x32x16_bf16 v[66:81], v[150:153], v[86:89], v[66:81]
	v_exp_f32_e32 v103, v103
	v_exp_f32_e32 v104, v104
	v_exp_f32_e32 v105, v105
	v_exp_f32_e32 v106, v106
	v_exp_f32_e32 v107, v107
	v_mfma_f32_32x32x16_bf16 v[50:65], v[158:161], v[86:89], v[50:65]
	v_exp_f32_e32 v108, v108
	v_exp_f32_e32 v109, v109
	v_exp_f32_e32 v110, v110
	v_exp_f32_e32 v111, v111
	v_exp_f32_e32 v112, v112
	v_exp_f32_e32 v113, v113
	v_add_f32_e32 v182, v98, v182
	v_add_f32_e32 v182, v99, v182
	v_add_f32_e32 v182, v100, v182
	v_add_f32_e32 v182, v101, v182
	v_add_f32_e32 v182, v102, v182
	v_add_f32_e32 v182, v103, v182
	v_add_f32_e32 v182, v104, v182
	v_add_f32_e32 v182, v105, v182
	v_add_f32_e32 v182, v106, v182
	v_add_f32_e32 v182, v107, v182
	v_add_f32_e32 v182, v108, v182
	v_add_f32_e32 v182, v109, v182
	v_add_f32_e32 v182, v110, v182
	v_add_f32_e32 v182, v111, v182
	v_add_f32_e32 v182, v112, v182
	v_add_f32_e32 v182, v113, v182
	v_cvt_pk_bf16_f32 v98, v98, v99
	v_cvt_pk_bf16_f32 v99, v100, v101
	v_cvt_pk_bf16_f32 v100, v102, v103
	v_cvt_pk_bf16_f32 v101, v104, v105
	v_cvt_pk_bf16_f32 v102, v106, v107
	v_cvt_pk_bf16_f32 v103, v108, v109
	v_cvt_pk_bf16_f32 v104, v110, v111
	v_cvt_pk_bf16_f32 v105, v112, v113
	s_nop 1
	v_mfma_f32_32x32x16_bf16 v[34:49], v[146:149], v[98:101], v[34:49]
	v_mfma_f32_32x32x16_bf16 v[2:17], v[154:157], v[98:101], v[2:17]
	v_mfma_f32_32x32x16_bf16 v[34:49], v[150:153], v[102:105], v[34:49]
	v_mfma_f32_32x32x16_bf16 v[2:17], v[158:161], v[102:105], v[2:17]
	s_movk_i32 s43, 0x100
	s_add_i32 s42, s42, s94
	s_cmpk_gt_i32 s42, 0x1ff
	s_cselect_b64 s[70:71], -1, 0
	s_cmpk_lt_i32 s42, 0x200
	s_cselect_b32 s43, s42, -1
	s_and_b32 s44, s43, 31
	s_cmp_gt_i32 s43, -1
	s_cselect_b64 s[46:47], -1, 0
	v_add_co_u32_e64 v0, s[48:49], s44, -1
	s_and_b64 s[68:69], s[46:47], s[48:49]
	s_waitcnt vmcnt(0) lgkmcnt(0)
	s_barrier
	s_cmp_lt_i32 s43, 0
	s_cbranch_scc1 .Lqpf_pool
	s_and_b32 s98, s43, 31
	s_lshl_b32 s98, s98, 7
	s_add_i32 s98, s98, s33
	s_ashr_i32 s99, s43, 7
	s_lshl_b32 s99, s99, 12
	s_add_i32 s98, s98, s99
	s_lshl_b32 s98, s98, 11
	s_bfe_u32 s99, s43, 0x20005
	s_lshl_b32 s99, s99, 2
	v_readlane_b32 vcc_lo, v251, 40
	s_nop 3
	s_or_b32 s99, s99, vcc_lo
	s_lshl_b32 s99, s99, 7
	s_add_u32 s98, s98, s99
	v_lshl_add_u32 v252, v170, 11, s98
	v_readlane_b32 s98, v251, 63
	v_readlane_b32 s99, v250, 0
	s_nop 7
	global_load_dword v252, v252, s[98:99]
	s_branch .Lqpf_skip
.Lqpf_pool:
	v_readlane_b32 s98, v251, 39
	s_nop 3
	s_cmpk_gt_i32 s98, 0x1ff
	s_cbranch_scc1 .Lqpf_skip
	s_lshr_b32 s99, s98, 2
	s_lshl_b32 s99, s99, 17
	s_and_b32 s98, s98, 3
	s_lshl_b32 s98, s98, 8
	s_add_u32 s98, s98, s99
	s_add_u32 s98, s98, 0x3100000
	v_lshrrev_b32_e32 v252, 1, v208
	v_subrev_u32_e32 v252, 8, v252
	v_lshlrev_b32_e32 v252, 10, v252
	v_and_b32_e32 v253, 1, v208
	v_lshl_add_u32 v252, v253, 7, v252
	v_add_u32_e32 v252, s98, v252
	v_readlane_b32 s98, v251, 63
	v_readlane_b32 s99, v250, 0
	v_cmp_gt_u32_e32 vcc, 0x120, v208
	s_nop 1
	s_and_b64 exec, exec, vcc
	s_cbranch_execz .Lqpf_pool_done
	s_nop 4
	global_load_dword v252, v252, s[98:99]
.Lqpf_pool_done:
	s_mov_b64 exec, -1
